# cross-half row-max exchange via v_permlane32_swap instead of ds_bpermute in the attention tile loops
# baseline (speedup 1.0000x reference)
.LBB0_1205:
	s_nop 8
	v_max3_f32 v1, v82, s48, v83
	v_max3_f32 v1, v1, v84, v85
	v_max3_f32 v1, v1, v86, v87
	v_max3_f32 v1, v1, v88, v89
	v_max3_f32 v1, v1, v90, v91
	v_max3_f32 v1, v1, v92, v93
	v_max3_f32 v1, v1, v94, v95
	v_max3_f32 v1, v1, v96, v97
	v_max3_f32 v1, v1, v66, v67
	v_max3_f32 v1, v1, v68, v69
	v_max3_f32 v1, v1, v70, v71
	v_max3_f32 v1, v1, v72, v73
	v_max3_f32 v1, v1, v74, v75
	v_max3_f32 v1, v1, v76, v77
	v_max3_f32 v1, v1, v78, v79
	v_max3_f32 v1, v1, v80, v81
	v_mov_b32_e32 v207, v1
	s_nop 1
	v_permlane32_swap_b32_e32 v207, v1
	s_waitcnt lgkmcnt(0)
	v_max_f32_e32 v207, v207, v207
	v_max_f32_e32 v1, v1, v207
	v_add_f32_e32 v207, 0x41000000, v249
	v_cmp_gt_f32_e32 vcc, v1, v207
	s_cbranch_vccz .LBB0_1200
	v_max_f32_e32 v1, v1, v1
	v_max_f32_e32 v250, v249, v249
	v_max_f32_e32 v250, v250, v1
	v_sub_f32_e32 v251, v250, v248
	v_sub_f32_e32 v206, v249, v250
	v_exp_f32_e32 v206, v206
	s_nop 0
	v_pk_mul_f32 v[64:65], v[64:65], v[206:207] op_sel_hi:[1,0]
	v_pk_mul_f32 v[62:63], v[62:63], v[206:207] op_sel_hi:[1,0]
	v_pk_mul_f32 v[60:61], v[60:61], v[206:207] op_sel_hi:[1,0]
	v_pk_mul_f32 v[58:59], v[58:59], v[206:207] op_sel_hi:[1,0]
	v_pk_mul_f32 v[56:57], v[56:57], v[206:207] op_sel_hi:[1,0]
	v_pk_mul_f32 v[54:55], v[54:55], v[206:207] op_sel_hi:[1,0]
	v_pk_mul_f32 v[52:53], v[52:53], v[206:207] op_sel_hi:[1,0]
	v_pk_mul_f32 v[50:51], v[50:51], v[206:207] op_sel_hi:[1,0]
	v_pk_mul_f32 v[48:49], v[48:49], v[206:207] op_sel_hi:[1,0]
	v_pk_mul_f32 v[46:47], v[46:47], v[206:207] op_sel_hi:[1,0]
	v_pk_mul_f32 v[44:45], v[44:45], v[206:207] op_sel_hi:[1,0]
	v_pk_mul_f32 v[42:43], v[42:43], v[206:207] op_sel_hi:[1,0]
	v_pk_mul_f32 v[40:41], v[40:41], v[206:207] op_sel_hi:[1,0]
	v_pk_mul_f32 v[38:39], v[38:39], v[206:207] op_sel_hi:[1,0]
	v_pk_mul_f32 v[36:37], v[36:37], v[206:207] op_sel_hi:[1,0]
	v_pk_mul_f32 v[34:35], v[34:35], v[206:207] op_sel_hi:[1,0]
	v_pk_mul_f32 v[32:33], v[32:33], v[206:207] op_sel_hi:[1,0]
	v_pk_mul_f32 v[30:31], v[30:31], v[206:207] op_sel_hi:[1,0]
	v_pk_mul_f32 v[28:29], v[28:29], v[206:207] op_sel_hi:[1,0]
	v_pk_mul_f32 v[26:27], v[26:27], v[206:207] op_sel_hi:[1,0]
	v_pk_mul_f32 v[24:25], v[24:25], v[206:207] op_sel_hi:[1,0]
	v_pk_mul_f32 v[22:23], v[22:23], v[206:207] op_sel_hi:[1,0]
	v_pk_mul_f32 v[20:21], v[20:21], v[206:207] op_sel_hi:[1,0]
	v_pk_mul_f32 v[18:19], v[18:19], v[206:207] op_sel_hi:[1,0]
	v_pk_mul_f32 v[16:17], v[16:17], v[206:207] op_sel_hi:[1,0]
	v_pk_mul_f32 v[14:15], v[14:15], v[206:207] op_sel_hi:[1,0]
	v_pk_mul_f32 v[12:13], v[12:13], v[206:207] op_sel_hi:[1,0]
	v_pk_mul_f32 v[10:11], v[10:11], v[206:207] op_sel_hi:[1,0]
	v_pk_mul_f32 v[8:9], v[8:9], v[206:207] op_sel_hi:[1,0]
	v_pk_mul_f32 v[6:7], v[6:7], v[206:207] op_sel_hi:[1,0]
	v_pk_mul_f32 v[4:5], v[4:5], v[206:207] op_sel_hi:[1,0]
	v_pk_mul_f32 v[2:3], v[2:3], v[206:207] op_sel_hi:[1,0]
	v_mul_f32_e32 v186, v186, v206
	v_mov_b32_e32 v206, v251
	v_xor_b32_e32 v250, 0x80000000, v251
	v_cmp_lt_f32_e32 vcc, 0xf0a18f08, v251
	s_nop 1
	v_cndmask_b32_e32 v250, 0, v250, vcc
	v_add_f32_e32 v249, v251, v250
	v_sub_f32_e32 v251, v250, v248
	v_mov_b32_e32 v248, v250
	v_add_f32_e32 v66, v251, v66
	v_add_f32_e32 v67, v251, v67
	v_add_f32_e32 v68, v251, v68
	v_add_f32_e32 v69, v251, v69
	v_add_f32_e32 v70, v251, v70
	v_add_f32_e32 v71, v251, v71
	v_add_f32_e32 v72, v251, v72
	v_add_f32_e32 v73, v251, v73
	v_add_f32_e32 v74, v251, v74
	v_add_f32_e32 v75, v251, v75
	v_add_f32_e32 v76, v251, v76
	v_add_f32_e32 v77, v251, v77
	v_add_f32_e32 v78, v251, v78
	v_add_f32_e32 v79, v251, v79
	v_add_f32_e32 v80, v251, v80
	v_add_f32_e32 v81, v251, v81
	v_add_f32_e32 v82, v251, v82
	v_add_f32_e32 v83, v251, v83
	v_add_f32_e32 v84, v251, v84
	v_add_f32_e32 v85, v251, v85
	v_add_f32_e32 v86, v251, v86
	v_add_f32_e32 v87, v251, v87
	v_add_f32_e32 v88, v251, v88
	v_add_f32_e32 v89, v251, v89
	v_add_f32_e32 v90, v251, v90
	v_add_f32_e32 v91, v251, v91
	v_add_f32_e32 v92, v251, v92
	v_add_f32_e32 v93, v251, v93
	v_add_f32_e32 v94, v251, v94
	v_add_f32_e32 v95, v251, v95
	v_add_f32_e32 v96, v251, v96
	v_add_f32_e32 v97, v251, v97
	v_mov_b32_e32 v232, v250
	v_mov_b32_e32 v233, v250
	v_mov_b32_e32 v234, v250
	v_mov_b32_e32 v235, v250
	v_mov_b32_e32 v236, v250
	v_mov_b32_e32 v237, v250
	v_mov_b32_e32 v238, v250
	v_mov_b32_e32 v239, v250
	v_mov_b32_e32 v240, v250
	v_mov_b32_e32 v241, v250
	v_mov_b32_e32 v242, v250
	v_mov_b32_e32 v243, v250
	v_mov_b32_e32 v244, v250
	v_mov_b32_e32 v245, v250
	v_mov_b32_e32 v246, v250
	v_mov_b32_e32 v247, v250
	s_branch .LBB0_1200

.LBB0_2149:
	s_nop 8
	v_max3_f32 v0, v50, s30, v51
	v_max3_f32 v0, v0, v52, v53
	v_max3_f32 v0, v0, v54, v55
	v_max3_f32 v0, v0, v56, v57
	v_max3_f32 v0, v0, v58, v59
	v_max3_f32 v0, v0, v60, v61
	v_max3_f32 v0, v0, v62, v63
	v_max3_f32 v0, v0, v64, v65
	v_max3_f32 v0, v0, v34, v35
	v_max3_f32 v0, v0, v36, v37
	v_max3_f32 v0, v0, v38, v39
	v_max3_f32 v0, v0, v40, v41
	v_max3_f32 v0, v0, v42, v43
	v_max3_f32 v0, v0, v44, v45
	v_max3_f32 v0, v0, v46, v47
	v_max3_f32 v0, v0, v48, v49
	v_mov_b32_e32 v145, v0
	s_nop 1
	v_permlane32_swap_b32_e32 v145, v0
	s_waitcnt lgkmcnt(0)
	v_max_f32_e32 v145, v145, v145
	v_max_f32_e32 v0, v0, v145
	v_add_f32_e32 v145, 0x41000000, v229
	v_cmp_gt_f32_e32 vcc, v0, v145
	s_cbranch_vccz .LBB0_2144
	v_max_f32_e32 v0, v0, v0
	v_max_f32_e32 v230, v229, v229
	v_max_f32_e32 v230, v230, v0
	v_sub_f32_e32 v231, v230, v228
	v_sub_f32_e32 v0, v229, v230
	v_exp_f32_e32 v0, v0
	s_nop 0
	v_pk_mul_f32 v[32:33], v[32:33], v[0:1] op_sel_hi:[1,0]
	v_pk_mul_f32 v[30:31], v[30:31], v[0:1] op_sel_hi:[1,0]
	v_pk_mul_f32 v[28:29], v[28:29], v[0:1] op_sel_hi:[1,0]
	v_pk_mul_f32 v[26:27], v[26:27], v[0:1] op_sel_hi:[1,0]
	v_pk_mul_f32 v[24:25], v[24:25], v[0:1] op_sel_hi:[1,0]
	v_pk_mul_f32 v[22:23], v[22:23], v[0:1] op_sel_hi:[1,0]
	v_pk_mul_f32 v[20:21], v[20:21], v[0:1] op_sel_hi:[1,0]
	v_pk_mul_f32 v[18:19], v[18:19], v[0:1] op_sel_hi:[1,0]
	v_pk_mul_f32 v[16:17], v[16:17], v[0:1] op_sel_hi:[1,0]
	v_pk_mul_f32 v[14:15], v[14:15], v[0:1] op_sel_hi:[1,0]
	v_pk_mul_f32 v[12:13], v[12:13], v[0:1] op_sel_hi:[1,0]
	v_pk_mul_f32 v[10:11], v[10:11], v[0:1] op_sel_hi:[1,0]
	v_pk_mul_f32 v[8:9], v[8:9], v[0:1] op_sel_hi:[1,0]
	v_pk_mul_f32 v[6:7], v[6:7], v[0:1] op_sel_hi:[1,0]
	v_pk_mul_f32 v[4:5], v[4:5], v[0:1] op_sel_hi:[1,0]
	v_pk_mul_f32 v[2:3], v[2:3], v[0:1] op_sel_hi:[1,0]
	v_mul_f32_e32 v101, v101, v0
	v_mov_b32_e32 v105, v231
	v_xor_b32_e32 v230, 0x80000000, v231
	v_cmp_lt_f32_e32 vcc, 0xf0a18f08, v231
	s_nop 1
	v_cndmask_b32_e32 v230, 0, v230, vcc
	v_add_f32_e32 v229, v231, v230
	v_sub_f32_e32 v231, v230, v228
	v_mov_b32_e32 v228, v230
	v_add_f32_e32 v34, v231, v34
	v_add_f32_e32 v35, v231, v35
	v_add_f32_e32 v36, v231, v36
	v_add_f32_e32 v37, v231, v37
	v_add_f32_e32 v38, v231, v38
	v_add_f32_e32 v39, v231, v39
	v_add_f32_e32 v40, v231, v40
	v_add_f32_e32 v41, v231, v41
	v_add_f32_e32 v42, v231, v42
	v_add_f32_e32 v43, v231, v43
	v_add_f32_e32 v44, v231, v44
	v_add_f32_e32 v45, v231, v45
	v_add_f32_e32 v46, v231, v46
	v_add_f32_e32 v47, v231, v47
	v_add_f32_e32 v48, v231, v48
	v_add_f32_e32 v49, v231, v49
	v_add_f32_e32 v50, v231, v50
	v_add_f32_e32 v51, v231, v51
	v_add_f32_e32 v52, v231, v52
	v_add_f32_e32 v53, v231, v53
	v_add_f32_e32 v54, v231, v54
	v_add_f32_e32 v55, v231, v55
	v_add_f32_e32 v56, v231, v56
	v_add_f32_e32 v57, v231, v57
	v_add_f32_e32 v58, v231, v58
	v_add_f32_e32 v59, v231, v59
	v_add_f32_e32 v60, v231, v60
	v_add_f32_e32 v61, v231, v61
	v_add_f32_e32 v62, v231, v62
	v_add_f32_e32 v63, v231, v63
	v_add_f32_e32 v64, v231, v64
	v_add_f32_e32 v65, v231, v65
	v_mov_b32_e32 v212, v230
	v_mov_b32_e32 v213, v230
	v_mov_b32_e32 v214, v230
	v_mov_b32_e32 v215, v230
	v_mov_b32_e32 v216, v230
	v_mov_b32_e32 v217, v230
	v_mov_b32_e32 v218, v230
	v_mov_b32_e32 v219, v230
	v_mov_b32_e32 v220, v230
	v_mov_b32_e32 v221, v230
	v_mov_b32_e32 v222, v230
	v_mov_b32_e32 v223, v230
	v_mov_b32_e32 v224, v230
	v_mov_b32_e32 v225, v230
	v_mov_b32_e32 v226, v230
	v_mov_b32_e32 v227, v230
	s_branch .LBB0_2144

.LBB0_4370:
	v_add3_u32 v0, s78, v102, v105
	s_waitcnt lgkmcnt(0)
	s_barrier
	ds_read_b128 v[2:5], v0
	ds_read_b128 v[18:21], v0 offset:32
	s_waitcnt lgkmcnt(1)
	v_mfma_f32_32x32x16_bf16 v[64:79], v[2:5], v[144:147], 0
	ds_read_b128 v[2:5], v0 offset:4608
	ds_read_b128 v[24:27], v0 offset:4640
	ds_read_b128 v[28:31], v0 offset:64
	ds_read_b128 v[110:113], v0 offset:96
	v_subrev_u32_e32 v22, 59, v104
	v_add_u32_e32 v23, 0xfffffc50, v103
	ds_read_b128 v[114:117], v0 offset:4672
	ds_read_b128 v[122:125], v0 offset:4704
	v_cmp_le_i32_e32 vcc, v23, v100
	v_cmp_gt_u32_e64 s[2:3], s65, v22
	s_waitcnt lgkmcnt(6)
	v_mfma_f32_32x32x16_bf16 v[64:79], v[18:21], v[148:151], v[64:79]
	v_subrev_u32_e32 v0, 58, v104
	v_add_u32_e32 v18, 0xfffffc60, v103
	v_subrev_u32_e32 v19, 57, v104
	v_add_u32_e32 v20, 0xfffffc70, v103
	v_cmp_le_i32_e64 s[4:5], v18, v100
	v_cmp_gt_u32_e64 s[6:7], s65, v0
	s_and_b64 vcc, s[2:3], vcc
	s_waitcnt lgkmcnt(3)
	v_mfma_f32_32x32x16_bf16 v[64:79], v[28:31], v[152:155], v[64:79]
	v_cmp_le_i32_e64 s[8:9], v20, v100
	v_subrev_u32_e32 v0, 56, v104
	v_add_u32_e32 v18, 0xfffffc80, v103
	v_cmp_gt_u32_e64 s[10:11], s65, v19
	v_cmp_le_i32_e64 s[12:13], v18, v100
	v_cmp_gt_u32_e64 s[14:15], s65, v0
	v_subrev_u32_e32 v21, 51, v104
	s_waitcnt lgkmcnt(2)
	v_mfma_f32_32x32x16_bf16 v[64:79], v[110:113], v[156:159], v[64:79]
	v_add_u32_e32 v22, 0xfffffcd0, v103
	v_cmp_gt_u32_e64 s[2:3], s65, v21
	v_subrev_u32_e32 v0, 50, v104
	v_add_u32_e32 v28, 0xfffffd70, v103
	v_add_u32_e32 v29, 0xfffffd80, v103
	v_add_u32_e32 v30, 0xfffffdd0, v103
	v_add_u32_e32 v31, 0xfffffde0, v103
	v_mfma_f32_32x32x16_bf16 v[2:17], v[2:5], v[144:147], 0
	s_nop 3
	v_cndmask_b32_e32 v23, v185, v64, vcc
	s_and_b64 vcc, s[6:7], s[4:5]
	v_cndmask_b32_e32 v20, v185, v65, vcc
	s_and_b64 vcc, s[10:11], s[8:9]
	v_cndmask_b32_e32 v19, v185, v66, vcc
	s_and_b64 vcc, s[14:15], s[12:13]
	v_cndmask_b32_e32 v18, v185, v67, vcc
	v_cmp_le_i32_e32 vcc, v22, v100
	s_and_b64 vcc, s[2:3], vcc
	v_add_u32_e32 v22, 0xfffffce0, v103
	v_mfma_f32_32x32x16_bf16 v[2:17], v[24:27], v[148:151], v[2:17]
	v_cndmask_b32_e32 v21, v185, v68, vcc
	v_cmp_le_i32_e32 vcc, v22, v100
	v_cmp_gt_u32_e64 s[2:3], s65, v0
	s_and_b64 vcc, s[2:3], vcc
	v_subrev_u32_e32 v0, 49, v104
	v_add_u32_e32 v24, 0xfffffcf0, v103
	v_cndmask_b32_e32 v22, v185, v69, vcc
	v_cmp_le_i32_e32 vcc, v24, v100
	v_cmp_gt_u32_e64 s[2:3], s65, v0
	s_and_b64 vcc, s[2:3], vcc
	v_subrev_u32_e32 v0, 48, v104
	v_add_u32_e32 v25, 0xfffffd00, v103
	v_cndmask_b32_e32 v24, v185, v70, vcc
	v_cmp_le_i32_e32 vcc, v25, v100
	v_cmp_gt_u32_e64 s[2:3], s65, v0
	s_and_b64 vcc, s[2:3], vcc
	v_subrev_u32_e32 v0, 43, v104
	v_add_u32_e32 v26, 0xfffffd50, v103
	v_cndmask_b32_e32 v25, v185, v71, vcc
	v_cmp_le_i32_e32 vcc, v26, v100
	v_cmp_gt_u32_e64 s[2:3], s65, v0
	s_and_b64 vcc, s[2:3], vcc
	v_subrev_u32_e32 v0, 42, v104
	v_add_u32_e32 v27, 0xfffffd60, v103
	s_waitcnt lgkmcnt(1)
	v_mfma_f32_32x32x16_bf16 v[2:17], v[114:117], v[152:155], v[2:17]
	v_cndmask_b32_e32 v26, v185, v72, vcc
	v_cmp_le_i32_e32 vcc, v27, v100
	v_cmp_gt_u32_e64 s[2:3], s65, v0
	s_and_b64 vcc, s[2:3], vcc
	v_subrev_u32_e32 v0, 41, v104
	v_cndmask_b32_e32 v27, v185, v73, vcc
	v_cmp_le_i32_e32 vcc, v28, v100
	v_cmp_gt_u32_e64 s[2:3], s65, v0
	s_and_b64 vcc, s[2:3], vcc
	v_subrev_u32_e32 v0, 40, v104
	v_cndmask_b32_e32 v28, v185, v74, vcc
	v_cmp_le_i32_e32 vcc, v29, v100
	v_cmp_gt_u32_e64 s[2:3], s65, v0
	s_and_b64 vcc, s[2:3], vcc
	v_subrev_u32_e32 v0, 35, v104
	v_cndmask_b32_e32 v29, v185, v75, vcc
	v_cmp_le_i32_e32 vcc, v30, v100
	v_cmp_gt_u32_e64 s[2:3], s65, v0
	s_and_b64 vcc, s[2:3], vcc
	v_subrev_u32_e32 v0, 34, v104
	s_waitcnt lgkmcnt(0)
	v_mfma_f32_32x32x16_bf16 v[2:17], v[122:125], v[156:159], v[2:17]
	v_cndmask_b32_e32 v30, v185, v76, vcc
	v_cmp_le_i32_e32 vcc, v31, v100
	v_cmp_gt_u32_e64 s[2:3], s65, v0
	s_and_b64 vcc, s[2:3], vcc
	v_subrev_u32_e32 v0, 33, v104
	v_add_u32_e32 v64, 0xfffffdf0, v103
	v_cndmask_b32_e32 v31, v185, v77, vcc
	v_cmp_le_i32_e32 vcc, v64, v100
	v_cmp_gt_u32_e64 s[2:3], s65, v0
	s_and_b64 vcc, s[2:3], vcc
	v_subrev_u32_e32 v0, 32, v104
	v_add_u32_e32 v65, 0xfffffe00, v103
	v_cndmask_b32_e32 v64, v185, v78, vcc
	v_cmp_le_i32_e32 vcc, v65, v100
	v_cmp_gt_u32_e64 s[2:3], s65, v0
	s_and_b64 vcc, s[2:3], vcc
	v_subrev_u32_e32 v0, 27, v104
	v_add_u32_e32 v66, 0xfffffe50, v103
	v_cndmask_b32_e32 v65, v185, v79, vcc
	v_cmp_le_i32_e32 vcc, v66, v100
	v_cmp_gt_u32_e64 s[2:3], s65, v0
	s_and_b64 vcc, s[2:3], vcc
	v_cndmask_b32_e32 v66, v185, v2, vcc
	v_subrev_u32_e32 v0, 26, v104
	v_add_u32_e32 v2, 0xfffffe60, v103
	v_cmp_le_i32_e32 vcc, v2, v100
	v_cmp_gt_u32_e64 s[2:3], s65, v0
	s_and_b64 vcc, s[2:3], vcc
	v_subrev_u32_e32 v0, 25, v104
	v_add_u32_e32 v2, 0xfffffe70, v103
	v_cndmask_b32_e32 v67, v185, v3, vcc
	v_cmp_le_i32_e32 vcc, v2, v100
	v_cmp_gt_u32_e64 s[2:3], s65, v0
	s_and_b64 vcc, s[2:3], vcc
	v_subrev_u32_e32 v0, 24, v104
	v_add_u32_e32 v2, 0xfffffe80, v103
	v_cndmask_b32_e32 v68, v185, v4, vcc
	v_cmp_le_i32_e32 vcc, v2, v100
	v_cmp_gt_u32_e64 s[2:3], s65, v0
	s_and_b64 vcc, s[2:3], vcc
	v_subrev_u32_e32 v0, 19, v104
	v_add_u32_e32 v2, 0xfffffed0, v103
	v_cndmask_b32_e32 v69, v185, v5, vcc
	v_cmp_le_i32_e32 vcc, v2, v100
	v_cmp_gt_u32_e64 s[2:3], s65, v0
	s_and_b64 vcc, s[2:3], vcc
	v_subrev_u32_e32 v0, 18, v104
	v_add_u32_e32 v2, 0xfffffee0, v103
	v_cndmask_b32_e32 v70, v185, v6, vcc
	v_cmp_le_i32_e32 vcc, v2, v100
	v_cmp_gt_u32_e64 s[2:3], s65, v0
	s_and_b64 vcc, s[2:3], vcc
	v_subrev_u32_e32 v0, 17, v104
	v_add_u32_e32 v2, 0xfffffef0, v103
	v_cndmask_b32_e32 v71, v185, v7, vcc
	v_cmp_le_i32_e32 vcc, v2, v100
	v_cmp_gt_u32_e64 s[2:3], s65, v0
	s_and_b64 vcc, s[2:3], vcc
	v_add_u32_e32 v0, -16, v104
	v_add_u32_e32 v2, 0xffffff00, v103
	v_cndmask_b32_e32 v72, v185, v8, vcc
	v_cmp_le_i32_e32 vcc, v2, v100
	v_cmp_gt_u32_e64 s[2:3], s65, v0
	s_and_b64 vcc, s[2:3], vcc
	v_add_u32_e32 v0, -11, v104
	v_add_u32_e32 v2, 0xffffff50, v103
	v_cndmask_b32_e32 v9, v185, v9, vcc
	v_cmp_le_i32_e32 vcc, v2, v100
	v_cmp_gt_u32_e64 s[2:3], s65, v0
	s_and_b64 vcc, s[2:3], vcc
	v_add_u32_e32 v0, -10, v104
	v_add_u32_e32 v2, 0xffffff60, v103
	v_cndmask_b32_e32 v8, v185, v10, vcc
	v_cmp_le_i32_e32 vcc, v2, v100
	v_cmp_gt_u32_e64 s[2:3], s65, v0
	v_max3_f32 v10, v23, s66, v20
	s_and_b64 vcc, s[2:3], vcc
	v_add_u32_e32 v0, -9, v104
	v_add_u32_e32 v2, 0xffffff70, v103
	v_max3_f32 v10, v10, v19, v18
	v_cndmask_b32_e32 v7, v185, v11, vcc
	v_cmp_le_i32_e32 vcc, v2, v100
	v_cmp_gt_u32_e64 s[2:3], s65, v0
	v_max3_f32 v10, v10, v21, v22
	s_and_b64 vcc, s[2:3], vcc
	v_add_u32_e32 v0, -8, v104
	v_add_u32_e32 v2, 0xffffff80, v103
	v_max3_f32 v10, v10, v24, v25
	v_cndmask_b32_e32 v6, v185, v12, vcc
	v_cmp_le_i32_e32 vcc, v2, v100
	v_cmp_gt_u32_e64 s[2:3], s65, v0
	v_max3_f32 v10, v10, v26, v27
	s_and_b64 vcc, s[2:3], vcc
	v_add_u32_e32 v0, -3, v104
	v_subrev_u32_e32 v2, 48, v103
	v_max3_f32 v10, v10, v28, v29
	v_cndmask_b32_e32 v4, v185, v13, vcc
	v_cmp_le_i32_e32 vcc, v2, v100
	v_cmp_gt_u32_e64 s[2:3], s65, v0
	v_max3_f32 v10, v10, v30, v31
	s_and_b64 vcc, s[2:3], vcc
	v_add_u32_e32 v0, -2, v104
	v_subrev_u32_e32 v2, 32, v103
	v_max3_f32 v10, v10, v64, v65
	v_cndmask_b32_e32 v5, v185, v14, vcc
	v_cmp_le_i32_e32 vcc, v2, v100
	v_cmp_gt_u32_e64 s[2:3], s65, v0
	v_max3_f32 v10, v10, v66, v67
	s_and_b64 vcc, s[2:3], vcc
	v_add_u32_e32 v0, -1, v104
	v_add_u32_e32 v2, -16, v103
	v_max3_f32 v10, v10, v68, v69
	v_cndmask_b32_e32 v3, v185, v15, vcc
	v_cmp_le_i32_e32 vcc, v2, v100
	v_cmp_gt_u32_e64 s[2:3], s65, v0
	v_max3_f32 v10, v10, v70, v71
	s_and_b64 vcc, s[2:3], vcc
	v_max3_f32 v10, v10, v72, v9
	v_cndmask_b32_e32 v0, v185, v16, vcc
	v_cmp_le_i32_e32 vcc, v103, v100
	v_cmp_gt_u32_e64 s[2:3], s65, v104
	v_max3_f32 v10, v10, v8, v7
	s_and_b64 vcc, s[2:3], vcc
	v_max3_f32 v10, v10, v6, v4
	v_cndmask_b32_e32 v2, v185, v17, vcc
	v_max3_f32 v10, v10, v5, v3
	v_max3_f32 v10, v10, v0, v2
	v_mov_b32_e32 v11, v10
	s_nop 1
	v_permlane32_swap_b32_e32 v11, v10
	s_waitcnt lgkmcnt(0)
	v_max_f32_e32 v11, v11, v11
	v_max_f32_e32 v10, v10, v11
	v_add_f32_e32 v11, 0x41000000, v108
	v_cmp_gt_f32_e32 vcc, v10, v11
	s_cbranch_vccz .LBB0_4367
	v_max_f32_e32 v10, v10, v10
	v_max_f32_e32 v11, v108, v108
	v_max_f32_e32 v11, v11, v10
	v_sub_f32_e32 v10, v108, v11
	v_exp_f32_e32 v10, v10
	v_mov_b32_e32 v108, v11
	v_pk_mul_f32 v[62:63], v[62:63], v[10:11] op_sel_hi:[1,0]
	v_pk_mul_f32 v[60:61], v[60:61], v[10:11] op_sel_hi:[1,0]
	v_pk_mul_f32 v[58:59], v[58:59], v[10:11] op_sel_hi:[1,0]
	v_pk_mul_f32 v[56:57], v[56:57], v[10:11] op_sel_hi:[1,0]
	v_pk_mul_f32 v[54:55], v[54:55], v[10:11] op_sel_hi:[1,0]
	v_pk_mul_f32 v[52:53], v[52:53], v[10:11] op_sel_hi:[1,0]
	v_pk_mul_f32 v[50:51], v[50:51], v[10:11] op_sel_hi:[1,0]
	v_pk_mul_f32 v[48:49], v[48:49], v[10:11] op_sel_hi:[1,0]
	v_pk_mul_f32 v[46:47], v[46:47], v[10:11] op_sel_hi:[1,0]
	v_pk_mul_f32 v[44:45], v[44:45], v[10:11] op_sel_hi:[1,0]
	v_pk_mul_f32 v[42:43], v[42:43], v[10:11] op_sel_hi:[1,0]
	v_pk_mul_f32 v[40:41], v[40:41], v[10:11] op_sel_hi:[1,0]
	v_pk_mul_f32 v[38:39], v[38:39], v[10:11] op_sel_hi:[1,0]
	v_pk_mul_f32 v[36:37], v[36:37], v[10:11] op_sel_hi:[1,0]
	v_pk_mul_f32 v[34:35], v[34:35], v[10:11] op_sel_hi:[1,0]
	v_pk_mul_f32 v[32:33], v[32:33], v[10:11] op_sel_hi:[1,0]
	v_mul_f32_e32 v99, v99, v10
	s_branch .LBB0_4367

.LBB0_4386:
	s_nop 8
	v_max3_f32 v0, v96, s66, v97
	v_max3_f32 v0, v0, v98, v99
	v_max3_f32 v0, v0, v100, v101
	v_max3_f32 v0, v0, v102, v103
	v_max3_f32 v0, v0, v104, v105
	v_max3_f32 v0, v0, v106, v107
	v_max3_f32 v0, v0, v108, v109
	v_max3_f32 v0, v0, v110, v111
	v_max3_f32 v0, v0, v2, v3
	v_max3_f32 v0, v0, v4, v5
	v_max3_f32 v0, v0, v6, v7
	v_max3_f32 v0, v0, v8, v9
	v_max3_f32 v0, v0, v10, v11
	v_max3_f32 v0, v0, v12, v13
	v_max3_f32 v0, v0, v14, v15
	v_max3_f32 v20, v0, v16, v17
	v_mov_b32_e32 v21, v20
	s_nop 1
	v_permlane32_swap_b32_e32 v21, v20
	v_lshrrev_b64 v[18:19], s2, v[120:121]
	v_and_b32_e32 v0, 1, v18
	v_cmp_eq_u64_e64 s[2:3], 0, v[0:1]
	s_waitcnt lgkmcnt(0)
	v_max_f32_e32 v18, v21, v21
	v_max_f32_e32 v18, v20, v18
	v_cndmask_b32_e64 v0, v18, v185, s[2:3]
	v_add_f32_e32 v18, 0x41000000, v139
	v_cmp_gt_f32_e32 vcc, v0, v18
	s_cbranch_vccz .LBB0_4388
	v_max_f32_e32 v0, v0, v0
	v_max_f32_e32 v18, v139, v139
	v_max_f32_e32 v18, v18, v0
	v_sub_f32_e32 v0, v139, v18
	v_exp_f32_e32 v0, v0
	v_mov_b32_e32 v139, v18
	v_pk_mul_f32 v[94:95], v[94:95], v[0:1] op_sel_hi:[1,0]
	v_pk_mul_f32 v[92:93], v[92:93], v[0:1] op_sel_hi:[1,0]
	v_pk_mul_f32 v[90:91], v[90:91], v[0:1] op_sel_hi:[1,0]
	v_pk_mul_f32 v[88:89], v[88:89], v[0:1] op_sel_hi:[1,0]
	v_pk_mul_f32 v[86:87], v[86:87], v[0:1] op_sel_hi:[1,0]
	v_pk_mul_f32 v[84:85], v[84:85], v[0:1] op_sel_hi:[1,0]
	v_pk_mul_f32 v[82:83], v[82:83], v[0:1] op_sel_hi:[1,0]
	v_pk_mul_f32 v[80:81], v[80:81], v[0:1] op_sel_hi:[1,0]
	v_pk_mul_f32 v[78:79], v[78:79], v[0:1] op_sel_hi:[1,0]
	v_pk_mul_f32 v[76:77], v[76:77], v[0:1] op_sel_hi:[1,0]
	v_pk_mul_f32 v[74:75], v[74:75], v[0:1] op_sel_hi:[1,0]
	v_pk_mul_f32 v[72:73], v[72:73], v[0:1] op_sel_hi:[1,0]
	v_pk_mul_f32 v[70:71], v[70:71], v[0:1] op_sel_hi:[1,0]
	v_pk_mul_f32 v[68:69], v[68:69], v[0:1] op_sel_hi:[1,0]
	v_pk_mul_f32 v[66:67], v[66:67], v[0:1] op_sel_hi:[1,0]
	v_pk_mul_f32 v[64:65], v[64:65], v[0:1] op_sel_hi:[1,0]
	v_mul_f32_e32 v189, v189, v0

.LBB0_4408:
	s_nop 8
	v_max3_f32 v0, v128, s66, v129
	v_max3_f32 v0, v0, v130, v131
	v_max3_f32 v0, v0, v132, v133
	v_max3_f32 v0, v0, v134, v135
	v_max3_f32 v0, v0, v136, v137
	v_max3_f32 v0, v0, v138, v139
	v_max3_f32 v0, v0, v140, v141
	v_max3_f32 v0, v0, v142, v143
	v_max3_f32 v0, v0, v2, v3
	v_max3_f32 v0, v0, v4, v5
	v_max3_f32 v0, v0, v6, v7
	v_max3_f32 v0, v0, v8, v9
	v_max3_f32 v0, v0, v10, v11
	v_max3_f32 v0, v0, v12, v13
	v_max3_f32 v0, v0, v14, v15
	v_max3_f32 v0, v0, v16, v17
	v_mov_b32_e32 v18, v0
	s_nop 1
	v_permlane32_swap_b32_e32 v18, v0
	s_waitcnt lgkmcnt(0)
	v_max_f32_e32 v18, v18, v18
	v_max_f32_e32 v0, v0, v18
	v_add_f32_e32 v18, 0x41000000, v229
	v_cmp_gt_f32_e32 vcc, v0, v18
	s_cbranch_vccz .LBB0_4403
	v_max_f32_e32 v0, v0, v0
	v_max_f32_e32 v230, v229, v229
	v_max_f32_e32 v230, v230, v0
	v_sub_f32_e32 v231, v230, v228
	v_sub_f32_e32 v0, v229, v230
	v_exp_f32_e32 v0, v0
	s_nop 0
	v_pk_mul_f32 v[126:127], v[126:127], v[0:1] op_sel_hi:[1,0]
	v_pk_mul_f32 v[124:125], v[124:125], v[0:1] op_sel_hi:[1,0]
	v_pk_mul_f32 v[122:123], v[122:123], v[0:1] op_sel_hi:[1,0]
	v_pk_mul_f32 v[120:121], v[120:121], v[0:1] op_sel_hi:[1,0]
	v_pk_mul_f32 v[118:119], v[118:119], v[0:1] op_sel_hi:[1,0]
	v_pk_mul_f32 v[116:117], v[116:117], v[0:1] op_sel_hi:[1,0]
	v_pk_mul_f32 v[114:115], v[114:115], v[0:1] op_sel_hi:[1,0]
	v_pk_mul_f32 v[112:113], v[112:113], v[0:1] op_sel_hi:[1,0]
	v_pk_mul_f32 v[110:111], v[110:111], v[0:1] op_sel_hi:[1,0]
	v_pk_mul_f32 v[108:109], v[108:109], v[0:1] op_sel_hi:[1,0]
	v_pk_mul_f32 v[106:107], v[106:107], v[0:1] op_sel_hi:[1,0]
	v_pk_mul_f32 v[104:105], v[104:105], v[0:1] op_sel_hi:[1,0]
	v_pk_mul_f32 v[102:103], v[102:103], v[0:1] op_sel_hi:[1,0]
	v_pk_mul_f32 v[100:101], v[100:101], v[0:1] op_sel_hi:[1,0]
	v_pk_mul_f32 v[98:99], v[98:99], v[0:1] op_sel_hi:[1,0]
	v_pk_mul_f32 v[96:97], v[96:97], v[0:1] op_sel_hi:[1,0]
	v_mul_f32_e32 v192, v192, v0
	v_mov_b32_e32 v200, v231
	v_xor_b32_e32 v230, 0x80000000, v231
	v_cmp_lt_f32_e32 vcc, 0xf0a18f08, v231
	s_nop 1
	v_cndmask_b32_e32 v230, 0, v230, vcc
	v_add_f32_e32 v229, v231, v230
	v_sub_f32_e32 v231, v230, v228
	v_mov_b32_e32 v228, v230
	v_add_f32_e32 v2, v231, v2
	v_add_f32_e32 v3, v231, v3
	v_add_f32_e32 v4, v231, v4
	v_add_f32_e32 v5, v231, v5
	v_add_f32_e32 v6, v231, v6
	v_add_f32_e32 v7, v231, v7
	v_add_f32_e32 v8, v231, v8
	v_add_f32_e32 v9, v231, v9
	v_add_f32_e32 v10, v231, v10
	v_add_f32_e32 v11, v231, v11
	v_add_f32_e32 v12, v231, v12
	v_add_f32_e32 v13, v231, v13
	v_add_f32_e32 v14, v231, v14
	v_add_f32_e32 v15, v231, v15
	v_add_f32_e32 v16, v231, v16
	v_add_f32_e32 v17, v231, v17
	v_add_f32_e32 v128, v231, v128
	v_add_f32_e32 v129, v231, v129
	v_add_f32_e32 v130, v231, v130
	v_add_f32_e32 v131, v231, v131
	v_add_f32_e32 v132, v231, v132
	v_add_f32_e32 v133, v231, v133
	v_add_f32_e32 v134, v231, v134
	v_add_f32_e32 v135, v231, v135
	v_add_f32_e32 v136, v231, v136
	v_add_f32_e32 v137, v231, v137
	v_add_f32_e32 v138, v231, v138
	v_add_f32_e32 v139, v231, v139
	v_add_f32_e32 v140, v231, v140
	v_add_f32_e32 v141, v231, v141
	v_add_f32_e32 v142, v231, v142
	v_add_f32_e32 v143, v231, v143
	v_mov_b32_e32 v212, v230
	v_mov_b32_e32 v213, v230
	v_mov_b32_e32 v214, v230
	v_mov_b32_e32 v215, v230
	v_mov_b32_e32 v216, v230
	v_mov_b32_e32 v217, v230
	v_mov_b32_e32 v218, v230
	v_mov_b32_e32 v219, v230
	v_mov_b32_e32 v220, v230
	v_mov_b32_e32 v221, v230
	v_mov_b32_e32 v222, v230
	v_mov_b32_e32 v223, v230
	v_mov_b32_e32 v224, v230
	v_mov_b32_e32 v225, v230
	v_mov_b32_e32 v226, v230
	v_mov_b32_e32 v227, v230
	s_branch .LBB0_4403
